# up-GEMM epilogue: per-row sum-of-squares dwords prefetched one unit ahead into v244-v251 (mid-epilogue, first unit in preamble); weight-load wait moved to first use
# speedup vs baseline: 1.0006x; 1.0006x over previous
;     __device__ __forceinline__ int a_row(const Unit& u) const { return (u.pm / 17) * 4096 + 254 * (u.pm % 17) - 2; }
; #define PG8_STAGE(bufoff, gbase, voff) do { _Pragma("unroll") for (int _i = 0; _i < 2; ++_i) \
;         __builtin_amdgcn_global_load_lds((const unsigned*)((const char*)(gbase) + (voff)[_i]), (PG8_LAS unsigned*)(lds + (bufoff) + ldsw + _i * 8192), 16, 0, 0); } while (0)
; #define PG8_WAIT_V(n) asm volatile("s_waitcnt vmcnt(" #n ")" ::: "memory")
; #define PG8_BAR __builtin_amdgcn_s_barrier()
;     __device__ __forceinline__ void operator()(const f32x4 (&acc)[2][2][4][2], const Unit& u, int wr, int wc, int fr, int fq) const {
;     ...
;         const int b = u.pm / 17, ti = u.pm % 17, t0 = 254 * ti - 2;
;         const int colx = wc * 32 + fq * 8, j0 = u.pn * 128 + colx;
;         float r2v[2][4]; f32x4 wts[2][2][4];
; #pragma unroll
;         for (int ai = 0; ai < 2; ++ai)
; #pragma unroll
;             for (int m = 0; m < 4; ++m) { int t = t0 + ai * HALF + wr * 64 + m * 16 + fr; t = t < 0 ? 0 : (t > 4095 ? 4095 : t); r2v[ai][m] = rowss[b * 4096 + t]; }
; template <class Epi, class Sched, bool ALIGN_EPI = false, bool SP2 = false>
; __device__ __forceinline__ void gemm_phase(PG8_LAS unsigned char* lds, const Gemm g, const Sched& S, const Epi& E) {
;     ...
;     const char* cA = (const char*)g.A + (long)S.a_row(cur) * (long)(K * 2); const char* cB = (const char*)g.Bt + (size_t)cur.pn * tstep;
;     S.a_ready(cur);
;     if constexpr (SP2) {
;         PG8_STAGE(PG8_SB(0, 0), cB, voffB); PG8_STAGE(PG8_SB(0, 1), cB + hstep, voffB); PG8_STAGE(PG8_SA(0, 0), cA, voffA); PG8_STAGE(PG8_SA(0, 1), cA + hstep, voffA);
;         if (wr == 1) PG8_BAR;
;         PG8_WAIT_V(2); PG8_BAR;
;         PG8_STAGE(PG8_SB(1, 0), cB + kstep, voffB); PG8_STAGE(PG8_SA(1, 0), cA + kstep, voffA); PG8_STAGE(PG8_SB(1, 1), cB + hstep + kstep, voffB);
;         PG8_WAIT_V(6); PG8_BAR;
;     } else {
;         PG8_STAGE(PG8_SB(0, 0), cB, voffB); PG8_STAGE(PG8_SA(0, 0), cA, voffA); PG8_STAGE(PG8_SB(0, 1), cB + hstep, voffB); PG8_STAGE(PG8_SA(0, 1), cA + hstep, voffA);
;         if (wr == 1) PG8_BAR;
;         PG8_WAIT_V(4); PG8_BAR;
;         PG8_STAGE(PG8_SB(1, 0), cB + kstep, voffB); PG8_STAGE(PG8_SA(1, 0), cA + kstep, voffA); PG8_STAGE(PG8_SB(1, 1), cB + hstep + kstep, voffB);
;         PG8_WAIT_V(6); PG8_BAR;
;     }
.LBB0_881:
	s_lshl_b32 s4, s4, 5
	s_mov_b64 s[44:45], 0x80
	s_and_b32 s7, s4, 0x60
	s_add_i32 m0, s94, 0x18000
	v_lshl_add_u64 v[6:7], v[6:7], 0, s[44:45]
	s_lshl_b32 s6, s92, 13
	s_lshl_b32 s8, s7, 7
	s_waitcnt vmcnt(2)
	s_barrier
	global_load_lds_dwordx4 v[6:7], off
	v_lshl_add_u64 v[4:5], v[4:5], 0, s[44:45]
	s_add_i32 m0, s94, 0x1a000
	s_add_i32 s91, s94, 0x8000
	s_add_i32 s24, s94, 0xa000
	global_load_lds_dwordx4 v[4:5], off
	v_lshl_add_u64 v[2:3], v[2:3], 0, s[44:45]
	s_mov_b32 m0, s91
	s_add_u32 s4, s66, 0x80080
	global_load_lds_dwordx4 v[2:3], off
	v_lshl_add_u64 v[0:1], v[0:1], 0, s[44:45]
	s_mov_b32 m0, s24
	s_addc_u32 s5, s67, 0
	global_load_lds_dwordx4 v[0:1], off
	s_add_i32 m0, s94, 0x1c000
	v_lshl_add_u64 v[0:1], s[4:5], 0, v[178:179]
	global_load_lds_dwordx4 v[0:1], off
	v_lshl_add_u64 v[0:1], s[4:5], 0, v[182:183]
	s_add_i32 m0, s94, 0x1e000
	v_lshrrev_b32_e32 v16, 1, v9
	global_load_lds_dwordx4 v[0:1], off
	v_and_b32_e32 v16, 24, v16
	s_cmpk_lt_u32 s3, 0x100
	v_and_b32_e32 v15, 15, v9
	v_lshlrev_b32_e32 v17, 1, v16
	v_lshlrev_b32_e32 v0, 2, v9
	s_cselect_b64 s[4:5], -1, 0
	v_lshl_or_b32 v17, v15, 6, v17
	v_and_b32_e32 v0, 32, v0
	v_writelane_b32 v254, s4, 13
	v_bitop3_b32 v1, v17, s6, v0 bitop3:0xde
	v_or_b32_e32 v210, s7, v16
	v_writelane_b32 v254, s5, 14
	v_cmp_lt_u32_e64 s[4:5], 13, v15
	v_cmp_gt_u32_e64 s[6:7], 2, v15
	v_lshl_or_b32 v208, s92, 6, v15
	v_writelane_b32 v254, s4, 20
	v_cndmask_b32_e64 v211, 0, 1, s[0:1]
	s_and_b64 s[48:49], s[0:1], s[6:7]
	s_movk_i32 s1, 0xff81
	v_writelane_b32 v254, s5, 21
	v_cmp_lt_i32_e64 s[4:5], s1, v208
	s_movk_i32 s1, 0xff71
	v_cmp_lt_i32_e64 s[12:13], s1, v208
	s_movk_i32 s1, 0xff61
	s_add_i32 s0, 0, 0x20000
	v_writelane_b32 v254, s12, 22
	s_cmp_gt_i32 s92, -1
	s_cselect_b64 s[52:53], -1, 0
	v_writelane_b32 v254, s13, 23
	v_cmp_lt_i32_e64 s[12:13], s1, v208
	v_bitop3_b32 v209, v17, s8, v0 bitop3:0xde
	v_lshlrev_b32_e32 v0, 10, v15
	v_writelane_b32 v254, s12, 24
	v_lshl_add_u32 v2, s92, 11, v0
	v_lshlrev_b32_e32 v3, 11, v211
	v_writelane_b32 v254, s13, 25
	s_movk_i32 s1, 0xff51
	v_readlane_b32 s26, v254, 11
	v_readlane_b32 s27, v254, 12
	v_readlane_b32 s56, v254, 0
	s_ashr_i32 s25, s26, 31
	s_ashr_i32 s27, s2, 31
	v_readlane_b32 s58, v254, 2
	v_readlane_b32 s59, v254, 3
	s_add_u32 s54, s58, 0xb000
	s_addc_u32 s55, s59, 0
	v_readlane_b32 s57, v254, 1
	s_add_u32 s56, s58, 0x16000
	v_add_u32_e32 v2, 0xffffc800, v2
	v_add_u32_e32 v3, s0, v3
	v_cmp_lt_i32_e64 s[20:21], s1, v208
	s_addc_u32 s57, s59, 0
	v_lshlrev_b32_e32 v4, 2, v210
	s_add_i32 s1, 0, 0x21000
	v_add3_u32 v215, s0, v2, v4
	v_add3_u32 v216, s1, v2, v4
	v_add_u32_e32 v2, 0xfffff800, v3
	s_add_i32 s0, s0, s22
	v_add_u32_e32 v217, v2, v4
	v_add_u32_e32 v219, s0, v4
	v_add_u32_e32 v218, v217, v0
	v_add_u32_e32 v220, v219, v0
	v_lshlrev_b32_e32 v0, 15, v8
	v_and_b32_e32 v0, 0xffff0000, v0
	v_lshl_add_u32 v0, v10, 12, v0
	v_and_b32_e32 v2, 1, v8
	v_lshl_or_b32 v0, v2, 6, v0
	v_lshl_add_u32 v184, v11, 1, v0
	v_lshlrev_b32_e32 v0, 15, v12
	v_and_b32_e32 v0, 0xffff0000, v0
	s_waitcnt vmcnt(6)
	v_lshl_add_u32 v0, v13, 12, v0
	v_and_b32_e32 v2, 1, v12
	v_lshl_or_b32 v0, v2, 6, v0
	s_add_i32 s90, 0, 0x10000
	s_add_i32 s3, 0, 0x14000
	v_cmp_eq_u32_e64 s[8:9], 0, v15
	v_cmp_lt_u32_e64 s[10:11], 1, v15
	v_cmp_lt_i32_e64 s[46:47], 1, v208
	v_or_b32_e32 v212, 16, v208
	v_or_b32_e32 v213, 32, v208
	v_or_b32_e32 v214, 48, v208
	v_mov_b32_e32 v185, v179
	v_lshl_add_u32 v186, v14, 1, v0
	v_mov_b32_e32 v187, v179
	v_mov_b64_e32 v[188:189], 0x5d8
	v_mov_b64_e32 v[190:191], 0x5d7
	v_add_u32_e32 v221, s90, v209
	v_add_u32_e32 v222, s3, v209
	v_add_u32_e32 v223, 0, v1
	s_movk_i32 s34, 0x5000
	v_mov_b32_e32 v224, 0x358637bd
	s_mov_b32 s35, 0x800000
	s_movk_i32 s68, 0x1000
	s_movk_i32 s69, 0x2c00
	v_mov_b32_e32 v225, 0xfff
	s_barrier
	v_readlane_b32 s60, v254, 4
	v_readlane_b32 s61, v254, 5
	v_readlane_b32 s62, v254, 6
	v_readlane_b32 s63, v254, 7
	s_mul_hi_i32 s100, s71, 0x78787879
	s_lshr_b32 s101, s100, 31
	s_ashr_i32 s100, s100, 3
	s_add_i32 s100, s100, s101
	s_mul_i32 s101, s100, 17
	s_sub_i32 s101, s71, s101
	s_mulk_i32 s101, 0xfe
	s_add_i32 s101, s101, -2
	s_lshl_b32 s100, s100, 12
	v_add_u32_e32 v252, s101, v208
	v_med3_i32 v253, v252, 0, v225
	v_or_b32_e32 v253, s100, v253
	v_lshlrev_b32_e32 v253, 2, v253
	global_load_dword v244, v253, s[40:41]
	v_max_i32_e32 v253, -16, v252
	v_add_u32_e32 v253, 16, v253
	v_min_u32_e32 v253, 0xfff, v253
	v_or_b32_e32 v253, s100, v253
	v_lshlrev_b32_e32 v253, 2, v253
	global_load_dword v245, v253, s[40:41]
	v_max_i32_e32 v253, 0xffffffe0, v252
	v_add_u32_e32 v253, 32, v253
	v_min_u32_e32 v253, 0xfff, v253
	v_or_b32_e32 v253, s100, v253
	v_lshlrev_b32_e32 v253, 2, v253
	global_load_dword v246, v253, s[40:41]
	v_max_i32_e32 v253, 0xffffffd0, v252
	v_add_u32_e32 v253, 48, v253
	v_min_u32_e32 v253, 0xfff, v253
	v_or_b32_e32 v253, s100, v253
	v_lshlrev_b32_e32 v253, 2, v253
	global_load_dword v247, v253, s[40:41]
	v_max_i32_e32 v253, 0xffffff80, v252
	v_add_u32_e32 v253, 0x80, v253
	v_min_u32_e32 v253, 0xfff, v253
	v_or_b32_e32 v253, s100, v253
	v_lshlrev_b32_e32 v253, 2, v253
	global_load_dword v248, v253, s[40:41]
	v_max_i32_e32 v253, 0xffffff70, v252
	v_add_u32_e32 v253, 0x90, v253
	v_min_u32_e32 v253, 0xfff, v253
	v_or_b32_e32 v253, s100, v253
	v_lshlrev_b32_e32 v253, 2, v253
	global_load_dword v249, v253, s[40:41]
	v_max_i32_e32 v253, 0xffffff60, v252
	v_add_u32_e32 v253, 0xa0, v253
	v_min_u32_e32 v253, 0xfff, v253
	v_or_b32_e32 v253, s100, v253
	v_lshlrev_b32_e32 v253, 2, v253
	global_load_dword v250, v253, s[40:41]
	v_max_i32_e32 v253, 0xffffff50, v252
	v_add_u32_e32 v253, 0xb0, v253
	v_min_u32_e32 v253, 0xfff, v253
	v_or_b32_e32 v253, s100, v253
	v_lshlrev_b32_e32 v253, 2, v253
	global_load_dword v251, v253, s[40:41]
	s_branch .LBB0_884

; #define PG8_LAS __attribute__((address_space(3)))
;     __device__ __forceinline__ void operator()(const f32x4 (&acc)[2][2][4][2], const Unit& u, int wr, int wc, int fr, int fq) const {
;     ...
;         const int b = u.pm / 17, ti = u.pm % 17, t0 = 254 * ti - 2;
;         const int colx = wc * 32 + fq * 8, j0 = u.pn * 128 + colx;
;         float r2v[2][4]; f32x4 wts[2][2][4];
; #pragma unroll
;         for (int ai = 0; ai < 2; ++ai)
; #pragma unroll
;             for (int m = 0; m < 4; ++m) { int t = t0 + ai * HALF + wr * 64 + m * 16 + fr; t = t < 0 ? 0 : (t > 4095 ? 4095 : t); r2v[ai][m] = rowss[b * 4096 + t]; }
; #pragma unroll
;         for (int bj = 0; bj < 2; ++bj) { const int c = bj * FF + j0;
;             wts[0][bj][0] = *(const f32x4*)(fw + c); wts[0][bj][1] = *(const f32x4*)(fw + 2 * FF + c); wts[0][bj][2] = *(const f32x4*)(fw + 4 * FF + c); wts[0][bj][3] = *(const f32x4*)(fb + c); }
; #pragma unroll
;         for (int ai = 0; ai < 2; ++ai)
; #pragma unroll
;             for (int m = 0; m < 4; ++m) r2v[ai][m] = rsqrtf(r2v[ai][m] * (1.f / 2048.f) + 1e-6f);
;         if (fr >= 14) {
; #pragma unroll
;             for (int ai = 0; ai < 2; ++ai)
; #pragma unroll
;                 for (int bj = 0; bj < 2; ++bj)
; #pragma unroll
;                     for (int n = 0; n < 2; ++n) *(PG8_LAS f32x4*)(xch + (((ai * 2 + wr) * 2 + (fr - 14)) * 256 + bj * 128 + colx + n * 4)) = acc[ai][bj][3][n] * r2v[ai][3];
.LBB0_892:
	s_mul_hi_i32 s0, s71, 0x78787879
	s_lshr_b32 s1, s0, 31
	s_ashr_i32 s0, s0, 3
	s_add_i32 s0, s0, s1
	s_mul_i32 s1, s0, 17
	s_sub_i32 s65, s71, s1
	s_mul_i32 s71, s65, 0xfe
	s_add_i32 s71, s71, -2
	v_add_u32_e32 v201, s71, v208
	s_lshl_b32 s59, s0, 12
	v_lshl_or_b32 v192, s64, 7, v210
	v_ashrrev_i32_e32 v193, 31, v192
	v_readlane_b32 s72, v254, 0
	v_lshlrev_b64 v[120:121], 2, v[192:193]
	v_readlane_b32 s74, v254, 2
	v_readlane_b32 s75, v254, 3
	v_readlane_b32 s76, v254, 4
	v_readlane_b32 s77, v254, 5
	v_lshl_add_u64 v[202:203], s[74:75], 0, v[120:121]
	v_lshl_add_u64 v[122:123], s[54:55], 0, v[120:121]
	v_lshl_add_u64 v[128:129], s[56:57], 0, v[120:121]
	v_lshl_add_u64 v[206:207], s[76:77], 0, v[120:121]
	v_add_co_u32_e32 v120, vcc, s34, v202
	global_load_dwordx4 v[136:139], v[202:203], off
	s_nop 0
	v_addc_co_u32_e32 v121, vcc, 0, v203, vcc
	v_add_co_u32_e32 v124, vcc, s34, v122
	global_load_dwordx4 v[144:147], v[122:123], off
	global_load_dwordx4 v[148:151], v[128:129], off
	v_addc_co_u32_e32 v125, vcc, 0, v123, vcc
	v_add_co_u32_e32 v128, vcc, s34, v128
	global_load_dwordx4 v[152:155], v[206:207], off
	s_nop 0
	v_addc_co_u32_e32 v129, vcc, 0, v129, vcc
	v_add_co_u32_e32 v132, vcc, s34, v206
	global_load_dwordx4 v[120:123], v[120:121], off offset:2048
	s_nop 0
	global_load_dwordx4 v[124:127], v[124:125], off offset:2048
	v_addc_co_u32_e32 v133, vcc, 0, v207, vcc
	global_load_dwordx4 v[128:131], v[128:129], off offset:2048
	v_readlane_b32 s12, v254, 20
	global_load_dwordx4 v[132:135], v[132:133], off offset:2048
	v_readlane_b32 s13, v254, 21
	v_readlane_b32 s73, v254, 1
	v_readlane_b32 s78, v254, 6
	v_readlane_b32 s79, v254, 7
	v_fmamk_f32 v160, v247, 0x3a000000, v224
	v_mul_f32_e32 v162, 0x4b800000, v160
	v_cmp_gt_f32_e32 vcc, s35, v160
	v_fmamk_f32 v161, v251, 0x3a000000, v224
	s_nop 0
	v_cndmask_b32_e32 v160, v160, v162, vcc
	v_mul_f32_e32 v162, 0x4b800000, v161
	v_cmp_gt_f32_e64 s[0:1], s35, v161
	v_rsq_f32_e32 v160, v160
	s_nop 0
	v_cndmask_b32_e64 v161, v161, v162, s[0:1]
	v_rsq_f32_e32 v161, v161
	v_mul_f32_e32 v162, 0x45800000, v160
	v_cndmask_b32_e32 v196, v160, v162, vcc
	v_mul_f32_e32 v160, 0x45800000, v161
	v_cndmask_b32_e64 v194, v161, v160, s[0:1]
	s_and_saveexec_b64 s[0:1], s[12:13]
	s_cbranch_execz .LBB0_894
	v_pk_mul_f32 v[162:163], v[74:75], v[196:197] op_sel_hi:[1,0]
	v_pk_mul_f32 v[160:161], v[72:73], v[196:197] op_sel_hi:[1,0]
	ds_write_b128 v215, v[160:163]
	v_pk_mul_f32 v[162:163], v[38:39], v[196:197] op_sel_hi:[1,0]
	v_pk_mul_f32 v[160:161], v[36:37], v[196:197] op_sel_hi:[1,0]
	ds_write_b128 v215, v[160:163] offset:16
	v_pk_mul_f32 v[162:163], v[70:71], v[196:197] op_sel_hi:[1,0]
	v_pk_mul_f32 v[160:161], v[68:69], v[196:197] op_sel_hi:[1,0]
	ds_write_b128 v215, v[160:163] offset:512
	v_pk_mul_f32 v[162:163], v[34:35], v[196:197] op_sel_hi:[1,0]
	v_pk_mul_f32 v[160:161], v[32:33], v[196:197] op_sel_hi:[1,0]
	ds_write_b128 v215, v[160:163] offset:528
	v_pk_mul_f32 v[162:163], v[78:79], v[194:195] op_sel_hi:[1,0]
	v_pk_mul_f32 v[160:161], v[76:77], v[194:195] op_sel_hi:[1,0]
	ds_write_b128 v216, v[160:163]
	v_pk_mul_f32 v[162:163], v[6:7], v[194:195] op_sel_hi:[1,0]
	v_pk_mul_f32 v[160:161], v[4:5], v[194:195] op_sel_hi:[1,0]
	ds_write_b128 v215, v[160:163] offset:4112
	v_pk_mul_f32 v[162:163], v[66:67], v[194:195] op_sel_hi:[1,0]
	v_pk_mul_f32 v[160:161], v[64:65], v[194:195] op_sel_hi:[1,0]
	ds_write_b128 v215, v[160:163] offset:4608
	v_pk_mul_f32 v[162:163], v[2:3], v[194:195] op_sel_hi:[1,0]
	v_pk_mul_f32 v[160:161], v[0:1], v[194:195] op_sel_hi:[1,0]
	ds_write_b128 v215, v[160:163] offset:4624

; #define PG8_LAS __attribute__((address_space(3)))
; __device__ __forceinline__ unsigned cvt_pk_bf16(float lo, float hi) { unsigned r; asm volatile("v_cvt_pk_bf16_f32 %0, %1, %2" : "=v"(r) : "v"(lo), "v"(hi)); return r; }
;     __device__ __forceinline__ void operator()(const f32x4 (&acc)[2][2][4][2], const Unit& u, int wr, int wc, int fr, int fq) const {
;     ...
;             for (int ai = 0; ai < 2; ++ai) {
;                 f32x4 pr1[2] = {zero4, zero4}, pr2[2] = {zero4, zero4};
;                 const bool hasprev = (wr == 1) || (ai == 1);
;                 const int pg = (wr == 1) ? ai * 2 : (ai - 1) * 2 + 1;
;                 if (hasprev && fr < 2) {
; #pragma unroll
;                     for (int bj = 0; bj < 2; ++bj) {
;                         pr2[bj] = *(const PG8_LAS f32x4*)(xch + ((pg * 2 + fr) * 256 + bj * 128 + colx + n * 4));
;                         pr1[bj] = *(const PG8_LAS f32x4*)(xch + ((pg * 2 + 1) * 256 + bj * 128 + colx + n * 4)); }
;                 }
; #pragma unroll
;                 for (int m = 0; m < 4; ++m) {
;                     f32x4 cur[2] = {acc[ai][0][m][n] * r2v[ai][m], acc[ai][1][m][n] * r2v[ai][m]};
;                     if (first && ai == 0 && wr == 0 && m == 0 && fr < 2) { cur[0] = zero4; cur[1] = zero4; }
;                     f32x4 r1[2], r2[2], av[2];
; #pragma unroll
;                     for (int bj = 0; bj < 2; ++bj)
; #pragma unroll
;                         for (int e = 0; e < 4; ++e) { r1[bj][e] = dpp_ror1(cur[bj][e]); r2[bj][e] = dpp_ror2(cur[bj][e]); }
; #pragma unroll
;                     for (int bj = 0; bj < 2; ++bj)
; #pragma unroll
;                         for (int e = 0; e < 4; ++e) { const float p1 = fr >= 1 ? r1[bj][e] : pr1[bj][e], p2 = fr >= 2 ? r2[bj][e] : pr2[bj][e];
;                             av[bj][e] = fma_s(w0[bj][e], p2, fma_s(w1[bj][e], p1, fma_s(w2[bj][e], cur[bj][e], bb[bj][e]))); }
;                     float o[4];
; #pragma unroll
;                     for (int e = 0; e < 4; ++e) o[e] = av[0][e] * sigmoid_f(av[0][e]) * av[1][e];
;                     const int lr = ai * HALF + wr * 64 + m * 16 + fr, t = t0 + lr;
;                     if (lr >= 2 && t < 4096) { u32x2 w; w.x = cvt_pk_bf16(o[0], o[1]); w.y = cvt_pk_bf16(o[2], o[3]);
;                         *(u32x2*)(gout + (size_t)(b * 4096 + t) * FF + j0 + n * 4) = w; }
.LBB0_896:
	s_or_b64 exec, exec, s[0:1]
	v_fmamk_f32 v198, v244, 0x3a000000, v224
	v_mul_f32_e32 v199, 0x4b800000, v198
	v_cmp_gt_f32_e32 vcc, s35, v198
	s_or_b32 s0, s65, s92
	s_cmp_eq_u32 s0, 0
	v_cndmask_b32_e32 v198, v198, v199, vcc
	v_rsq_f32_e32 v198, v198
	s_cselect_b64 s[0:1], -1, 0
	s_and_b64 s[78:79], s[0:1], s[6:7]
	v_mul_f32_e32 v199, 0x45800000, v198
	v_cndmask_b32_e32 v204, v198, v199, vcc
	v_pk_mul_f32 v[100:101], v[100:101], v[204:205] op_sel_hi:[1,0]
	v_pk_mul_f32 v[96:97], v[96:97], v[204:205] op_sel_hi:[1,0]
	v_pk_mul_f32 v[98:99], v[98:99], v[204:205] op_sel_hi:[1,0]
	v_cndmask_b32_e64 v241, v96, 0, s[78:79]
	v_cndmask_b32_e64 v96, v100, 0, s[78:79]
	v_pk_mul_f32 v[102:103], v[102:103], v[204:205] op_sel_hi:[1,0]
	v_cndmask_b32_e64 v200, v98, 0, s[78:79]
	v_cndmask_b32_e64 v98, v101, 0, s[78:79]
	v_mov_b32_dpp v238, v96 row_ror:1 row_mask:0xf bank_mask:0xf
	v_cndmask_b32_e64 v102, v102, 0, s[78:79]
	v_mov_b32_dpp v239, v96 row_ror:2 row_mask:0xf bank_mask:0xf
	v_mov_b32_dpp v236, v98 row_ror:1 row_mask:0xf bank_mask:0xf
	s_waitcnt vmcnt(0) lgkmcnt(1)
	v_cndmask_b32_e64 v100, v238, v168, s[8:9]
	v_fma_f32 v96, v148, v96, v152
	v_cndmask_b32_e64 v242, v103, 0, s[78:79]
	v_mov_b32_dpp v237, v98 row_ror:2 row_mask:0xf bank_mask:0xf
	v_mov_b32_dpp v234, v102 row_ror:1 row_mask:0xf bank_mask:0xf
	v_cndmask_b32_e64 v168, v172, v239, s[10:11]
	v_fma_f32 v96, v144, v100, v96
	v_cndmask_b32_e64 v100, v236, v169, s[8:9]
	v_fma_f32 v98, v149, v98, v153
	v_mov_b32_dpp v235, v102 row_ror:2 row_mask:0xf bank_mask:0xf
	v_mov_b32_dpp v232, v242 row_ror:1 row_mask:0xf bank_mask:0xf
	v_fma_f32 v96, v136, v168, v96
	v_cndmask_b32_e64 v168, v173, v237, s[10:11]
	v_fma_f32 v98, v145, v100, v98
	v_cndmask_b32_e64 v100, v234, v170, s[8:9]
	v_fma_f32 v102, v150, v102, v154
	v_mov_b32_dpp v233, v242 row_ror:2 row_mask:0xf bank_mask:0xf
	v_fma_f32 v98, v137, v168, v98
	v_cndmask_b32_e64 v168, v174, v235, s[10:11]
	v_fma_f32 v100, v146, v100, v102
	v_cndmask_b32_e64 v102, v232, v171, s[8:9]
	v_mov_b32_dpp v230, v241 row_ror:1 row_mask:0xf bank_mask:0xf
	v_fma_f32 v100, v138, v168, v100
	v_cndmask_b32_e64 v168, v175, v233, s[10:11]
	v_fma_f32 v169, v151, v242, v155
	v_cndmask_b32_e64 v240, v97, 0, s[78:79]
	v_fma_f32 v102, v147, v102, v169
	v_mov_b32_dpp v231, v241 row_ror:2 row_mask:0xf bank_mask:0xf
	v_fma_f32 v168, v139, v168, v102
	s_waitcnt lgkmcnt(0)
	v_cndmask_b32_e64 v102, v230, v160, s[8:9]
	v_mov_b32_dpp v198, v240 row_ror:1 row_mask:0xf bank_mask:0xf
	v_cndmask_b32_e64 v160, v164, v231, s[10:11]
	v_fma_f32 v164, v128, v241, v132
	v_mov_b32_dpp v227, v240 row_ror:2 row_mask:0xf bank_mask:0xf
	v_fma_f32 v102, v124, v102, v164
	v_fma_f32 v102, v120, v160, v102
	v_cndmask_b32_e64 v160, v198, v161, s[8:9]
	v_mov_b32_dpp v101, v200 row_ror:1 row_mask:0xf bank_mask:0xf
	v_cndmask_b32_e64 v161, v165, v227, s[10:11]
	v_fma_f32 v164, v129, v240, v133
	v_cndmask_b32_e64 v199, v99, 0, s[78:79]
	v_fma_f32 v160, v125, v160, v164
	v_mov_b32_dpp v103, v200 row_ror:2 row_mask:0xf bank_mask:0xf
	v_fma_f32 v160, v121, v161, v160
	v_cndmask_b32_e64 v161, v101, v162, s[8:9]
	v_cndmask_b32_e64 v162, v166, v103, s[10:11]
	v_mov_b32_dpp v97, v199 row_ror:1 row_mask:0xf bank_mask:0xf
	v_fma_f32 v164, v130, v200, v134
	v_fma_f32 v161, v126, v161, v164
	v_cmp_gt_i32_e32 vcc, s68, v201
	v_fma_f32 v161, v122, v162, v161
	v_cndmask_b32_e64 v162, v97, v163, s[8:9]
	v_mov_b32_dpp v99, v199 row_ror:2 row_mask:0xf bank_mask:0xf
	v_fma_f32 v164, v131, v199, v135
	s_and_b64 s[80:81], s[46:47], vcc
	v_fma_f32 v162, v127, v162, v164
	v_add_u32_e32 v199, s59, v201
	v_cndmask_b32_e64 v163, v167, v99, s[10:11]
	v_fma_f32 v162, v123, v163, v162
	s_and_saveexec_b64 s[0:1], s[80:81]
	s_cbranch_execz .LBB0_898
	v_mul_f32_e32 v163, 0xbfb8aa3b, v168
	v_exp_f32_e32 v163, v163
	v_mul_f32_e32 v164, 0xbfb8aa3b, v100
	v_exp_f32_e32 v164, v164
	v_mul_f32_e32 v165, 0xbfb8aa3b, v98
	v_add_f32_e32 v163, 1.0, v163
	v_rcp_f32_e32 v163, v163
	v_add_f32_e32 v164, 1.0, v164
	v_exp_f32_e32 v165, v165
	v_rcp_f32_e32 v164, v164
	v_mul_f32_e32 v163, v168, v163
	v_mul_f32_e32 v162, v163, v162
	v_mul_f32_e32 v163, 0xbfb8aa3b, v96
	v_exp_f32_e32 v163, v163
	v_mul_f32_e32 v100, v100, v164
	v_add_f32_e32 v164, 1.0, v165
	v_rcp_f32_e32 v164, v164
	v_add_f32_e32 v163, 1.0, v163
	v_rcp_f32_e32 v163, v163
	v_mul_f32_e32 v100, v100, v161
	v_mul_f32_e32 v98, v98, v164
	v_mul_f32_e32 v98, v98, v160
	v_mul_f32_e32 v96, v96, v163
	v_mul_f32_e32 v96, v96, v102
	v_cvt_pk_bf16_f32 v160, v96, v98
	v_cvt_pk_bf16_f32 v161, v100, v162
	v_mov_b64_e32 v[162:163], s[36:37]
	v_mad_i64_i32 v[162:163], s[64:65], v199, s69, v[162:163]
	v_lshl_add_u64 v[162:163], v[192:193], 1, v[162:163]
	global_store_dwordx2 v[162:163], v[160:161], off
; __device__ __forceinline__ unsigned cvt_pk_bf16(float lo, float hi) { unsigned r; asm volatile("v_cvt_pk_bf16_f32 %0, %1, %2" : "=v"(r) : "v"(lo), "v"(hi)); return r; }
; __device__ __forceinline__ float sigmoid_f(float x) { return __builtin_amdgcn_rcpf(1.0f + __builtin_amdgcn_exp2f(-1.4426950408889634f * x)); }
; __device__ __forceinline__ float dpp_ror1(float v) { return __builtin_bit_cast(float, __builtin_amdgcn_update_dpp(0, __builtin_bit_cast(int, v), 0x121, 0xf, 0xf, false)); }
; __device__ __forceinline__ float dpp_ror2(float v) { return __builtin_bit_cast(float, __builtin_amdgcn_update_dpp(0, __builtin_bit_cast(int, v), 0x122, 0xf, 0xf, false)); }
; __device__ __forceinline__ float fma_s(float a, float b, float c) { float r; asm("v_fma_f32 %0, %1, %2, %3" : "=v"(r) : "v"(a), "v"(b), "v"(c)); return r; }
;     __device__ __forceinline__ void operator()(const f32x4 (&acc)[2][2][4][2], const Unit& u, int wr, int wc, int fr, int fq) const {
;     ...
;                 for (int m = 0; m < 4; ++m) {
;                     f32x4 cur[2] = {acc[ai][0][m][n] * r2v[ai][m], acc[ai][1][m][n] * r2v[ai][m]};
;                     if (first && ai == 0 && wr == 0 && m == 0 && fr < 2) { cur[0] = zero4; cur[1] = zero4; }
;                     f32x4 r1[2], r2[2], av[2];
; #pragma unroll
;                     for (int bj = 0; bj < 2; ++bj)
; #pragma unroll
;                         for (int e = 0; e < 4; ++e) { r1[bj][e] = dpp_ror1(cur[bj][e]); r2[bj][e] = dpp_ror2(cur[bj][e]); }
; #pragma unroll
;                     for (int bj = 0; bj < 2; ++bj)
; #pragma unroll
;                         for (int e = 0; e < 4; ++e) { const float p1 = fr >= 1 ? r1[bj][e] : pr1[bj][e], p2 = fr >= 2 ? r2[bj][e] : pr2[bj][e];
;                             av[bj][e] = fma_s(w0[bj][e], p2, fma_s(w1[bj][e], p1, fma_s(w2[bj][e], cur[bj][e], bb[bj][e]))); }
;                     float o[4];
; #pragma unroll
;                     for (int e = 0; e < 4; ++e) o[e] = av[0][e] * sigmoid_f(av[0][e]) * av[1][e];
;                     const int lr = ai * HALF + wr * 64 + m * 16 + fr, t = t0 + lr;
;                     if (lr >= 2 && t < 4096) { u32x2 w; w.x = cvt_pk_bf16(o[0], o[1]); w.y = cvt_pk_bf16(o[2], o[3]);
;                         *(u32x2*)(gout + (size_t)(b * 4096 + t) * FF + j0 + n * 4) = w; }
.LBB0_898:
	s_or_b64 exec, exec, s[0:1]
	v_fmamk_f32 v96, v245, 0x3a000000, v224
	v_mul_f32_e32 v98, 0x4b800000, v96
	v_cmp_gt_f32_e32 vcc, s35, v96
	s_nop 1
	v_cndmask_b32_e32 v96, v96, v98, vcc
	v_rsq_f32_e32 v96, v96
	s_nop 0
	v_mul_f32_e32 v98, 0x45800000, v96
	v_cndmask_b32_e32 v200, v96, v98, vcc
	v_pk_mul_f32 v[92:93], v[92:93], v[200:201] op_sel_hi:[1,0]
	v_pk_mul_f32 v[174:175], v[88:89], v[200:201] op_sel_hi:[1,0]
	v_pk_mul_f32 v[172:173], v[90:91], v[200:201] op_sel_hi:[1,0]
	v_mov_b32_dpp v170, v92 row_ror:1 row_mask:0xf bank_mask:0xf
	v_mov_b32_dpp v171, v92 row_ror:2 row_mask:0xf bank_mask:0xf
	v_cndmask_b32_e64 v88, v170, v238, s[8:9]
	v_mov_b32_dpp v168, v93 row_ror:1 row_mask:0xf bank_mask:0xf
	v_cndmask_b32_e64 v89, v239, v171, s[10:11]
	v_fma_f32 v90, v148, v92, v152
	v_pk_mul_f32 v[94:95], v[94:95], v[200:201] op_sel_hi:[1,0]
	v_fma_f32 v88, v144, v88, v90
	v_mov_b32_dpp v169, v93 row_ror:2 row_mask:0xf bank_mask:0xf
	v_fma_f32 v88, v136, v89, v88
	v_cndmask_b32_e64 v89, v168, v236, s[8:9]
	v_mov_b32_dpp v166, v94 row_ror:1 row_mask:0xf bank_mask:0xf
	v_cndmask_b32_e64 v90, v237, v169, s[10:11]
	v_fma_f32 v91, v149, v93, v153
	v_fma_f32 v89, v145, v89, v91
	v_mov_b32_dpp v167, v94 row_ror:2 row_mask:0xf bank_mask:0xf
	v_fma_f32 v89, v137, v90, v89
	v_cndmask_b32_e64 v90, v166, v234, s[8:9]
	v_mov_b32_dpp v163, v95 row_ror:1 row_mask:0xf bank_mask:0xf
	v_cndmask_b32_e64 v91, v235, v167, s[10:11]
	v_fma_f32 v92, v150, v94, v154
	v_fma_f32 v90, v146, v90, v92
	v_mov_b32_dpp v165, v95 row_ror:2 row_mask:0xf bank_mask:0xf
	v_fma_f32 v90, v138, v91, v90
	v_cndmask_b32_e64 v91, v163, v232, s[8:9]
	v_mov_b32_dpp v162, v174 row_ror:1 row_mask:0xf bank_mask:0xf
	v_cndmask_b32_e64 v92, v233, v165, s[10:11]
	v_fma_f32 v93, v151, v95, v155
	v_fma_f32 v91, v147, v91, v93
	v_mov_b32_dpp v164, v174 row_ror:2 row_mask:0xf bank_mask:0xf
	v_fma_f32 v92, v139, v92, v91
	v_cndmask_b32_e64 v91, v162, v230, s[8:9]
	v_mov_b32_dpp v160, v175 row_ror:1 row_mask:0xf bank_mask:0xf
	v_cndmask_b32_e64 v93, v231, v164, s[10:11]
	v_fma_f32 v94, v128, v174, v132
	v_fma_f32 v91, v124, v91, v94
	v_mov_b32_dpp v161, v175 row_ror:2 row_mask:0xf bank_mask:0xf
	v_fma_f32 v91, v120, v93, v91
	v_cndmask_b32_e64 v93, v160, v198, s[8:9]
	v_mov_b32_dpp v100, v172 row_ror:1 row_mask:0xf bank_mask:0xf
	v_cndmask_b32_e64 v94, v227, v161, s[10:11]
	v_fma_f32 v95, v129, v175, v133
	v_fma_f32 v93, v125, v93, v95
	v_mov_b32_dpp v102, v172 row_ror:2 row_mask:0xf bank_mask:0xf
	v_fma_f32 v93, v121, v94, v93
	v_cndmask_b32_e64 v94, v100, v101, s[8:9]
	v_mov_b32_dpp v96, v173 row_ror:1 row_mask:0xf bank_mask:0xf
	v_cndmask_b32_e64 v95, v103, v102, s[10:11]
	v_fma_f32 v101, v130, v172, v134
	s_nop 0
	v_fma_f32 v94, v126, v94, v101
	v_mov_b32_dpp v98, v173 row_ror:2 row_mask:0xf bank_mask:0xf
	v_fma_f32 v94, v122, v95, v94
	v_cndmask_b32_e64 v95, v96, v97, s[8:9]
	v_cndmask_b32_e64 v97, v99, v98, s[10:11]
	v_fma_f32 v99, v131, v173, v135
	s_nop 0
	v_fma_f32 v95, v127, v95, v99
	s_nop 0
	v_fma_f32 v95, v123, v97, v95
	v_add_u32_e32 v97, s71, v212
	v_cmp_gt_i32_e32 vcc, s68, v97
	s_and_b64 s[66:67], s[52:53], vcc
	v_add_u32_e32 v197, s59, v97
	s_and_saveexec_b64 s[0:1], s[66:67]
	s_cbranch_execz .LBB0_900
	v_mul_f32_e32 v97, 0xbfb8aa3b, v92
	v_exp_f32_e32 v97, v97
	v_mul_f32_e32 v99, 0xbfb8aa3b, v90
	v_mul_f32_e32 v101, 0xbfb8aa3b, v89
	v_exp_f32_e32 v99, v99
	v_add_f32_e32 v97, 1.0, v97
	v_rcp_f32_e32 v97, v97
	v_exp_f32_e32 v101, v101
	v_add_f32_e32 v99, 1.0, v99
	v_rcp_f32_e32 v99, v99
	v_mul_f32_e32 v92, v92, v97
	v_mul_f32_e32 v92, v92, v95
	v_mul_f32_e32 v95, 0xbfb8aa3b, v88
	v_exp_f32_e32 v95, v95
	v_add_f32_e32 v97, 1.0, v101
	v_rcp_f32_e32 v97, v97
	v_mul_f32_e32 v90, v90, v99
	v_add_f32_e32 v95, 1.0, v95
	v_rcp_f32_e32 v95, v95
	v_mul_f32_e32 v89, v89, v97
	v_mul_f32_e32 v90, v90, v94
	v_mul_f32_e32 v89, v89, v93
	v_mul_f32_e32 v88, v88, v95
	v_mul_f32_e32 v88, v88, v91
	v_cvt_pk_bf16_f32 v88, v88, v89
	v_cvt_pk_bf16_f32 v89, v90, v92
	v_mov_b64_e32 v[90:91], s[36:37]
	v_mad_i64_i32 v[90:91], s[64:65], v197, s69, v[90:91]
	v_lshl_add_u64 v[90:91], v[192:193], 1, v[90:91]
	global_store_dwordx2 v[90:91], v[88:89], off
; __device__ __forceinline__ unsigned cvt_pk_bf16(float lo, float hi) { unsigned r; asm volatile("v_cvt_pk_bf16_f32 %0, %1, %2" : "=v"(r) : "v"(lo), "v"(hi)); return r; }
; __device__ __forceinline__ float sigmoid_f(float x) { return __builtin_amdgcn_rcpf(1.0f + __builtin_amdgcn_exp2f(-1.4426950408889634f * x)); }
; __device__ __forceinline__ float dpp_ror1(float v) { return __builtin_bit_cast(float, __builtin_amdgcn_update_dpp(0, __builtin_bit_cast(int, v), 0x121, 0xf, 0xf, false)); }
; __device__ __forceinline__ float dpp_ror2(float v) { return __builtin_bit_cast(float, __builtin_amdgcn_update_dpp(0, __builtin_bit_cast(int, v), 0x122, 0xf, 0xf, false)); }
; __device__ __forceinline__ float fma_s(float a, float b, float c) { float r; asm("v_fma_f32 %0, %1, %2, %3" : "=v"(r) : "v"(a), "v"(b), "v"(c)); return r; }
;     __device__ __forceinline__ void operator()(const f32x4 (&acc)[2][2][4][2], const Unit& u, int wr, int wc, int fr, int fq) const {
;     ...
;                 for (int m = 0; m < 4; ++m) {
;                     f32x4 cur[2] = {acc[ai][0][m][n] * r2v[ai][m], acc[ai][1][m][n] * r2v[ai][m]};
;                     if (first && ai == 0 && wr == 0 && m == 0 && fr < 2) { cur[0] = zero4; cur[1] = zero4; }
;                     f32x4 r1[2], r2[2], av[2];
; #pragma unroll
;                     for (int bj = 0; bj < 2; ++bj)
; #pragma unroll
;                         for (int e = 0; e < 4; ++e) { r1[bj][e] = dpp_ror1(cur[bj][e]); r2[bj][e] = dpp_ror2(cur[bj][e]); }
; #pragma unroll
;                     for (int bj = 0; bj < 2; ++bj)
; #pragma unroll
;                         for (int e = 0; e < 4; ++e) { const float p1 = fr >= 1 ? r1[bj][e] : pr1[bj][e], p2 = fr >= 2 ? r2[bj][e] : pr2[bj][e];
;                             av[bj][e] = fma_s(w0[bj][e], p2, fma_s(w1[bj][e], p1, fma_s(w2[bj][e], cur[bj][e], bb[bj][e]))); }
;                     float o[4];
; #pragma unroll
;                     for (int e = 0; e < 4; ++e) o[e] = av[0][e] * sigmoid_f(av[0][e]) * av[1][e];
;                     const int lr = ai * HALF + wr * 64 + m * 16 + fr, t = t0 + lr;
;                     if (lr >= 2 && t < 4096) { u32x2 w; w.x = cvt_pk_bf16(o[0], o[1]); w.y = cvt_pk_bf16(o[2], o[3]);
;                         *(u32x2*)(gout + (size_t)(b * 4096 + t) * FF + j0 + n * 4) = w; }
.LBB0_900:
	s_or_b64 exec, exec, s[0:1]
	v_fmamk_f32 v88, v246, 0x3a000000, v224
	v_mul_f32_e32 v89, 0x4b800000, v88
	v_cmp_gt_f32_e32 vcc, s35, v88
	s_nop 1
	v_cndmask_b32_e32 v88, v88, v89, vcc
	v_rsq_f32_e32 v88, v88
	s_nop 0
	v_mul_f32_e32 v89, 0x45800000, v88
	v_cndmask_b32_e32 v198, v88, v89, vcc
	v_pk_mul_f32 v[174:175], v[84:85], v[198:199] op_sel_hi:[1,0]
	v_pk_mul_f32 v[172:173], v[86:87], v[198:199] op_sel_hi:[1,0]
	v_fma_f32 v101, v148, v174, v152
	v_fma_f32 v103, v149, v175, v153
	v_mov_b32_dpp v94, v174 row_ror:1 row_mask:0xf bank_mask:0xf
	v_mov_b32_dpp v95, v174 row_ror:2 row_mask:0xf bank_mask:0xf
	v_cndmask_b32_e64 v97, v94, v170, s[8:9]
	v_mov_b32_dpp v92, v175 row_ror:1 row_mask:0xf bank_mask:0xf
	v_cndmask_b32_e64 v99, v171, v95, s[10:11]
	v_fma_f32 v97, v144, v97, v101
	v_mov_b32_dpp v93, v175 row_ror:2 row_mask:0xf bank_mask:0xf
	v_fma_f32 v97, v136, v99, v97
	v_cndmask_b32_e64 v99, v92, v168, s[8:9]
	v_mov_b32_dpp v90, v172 row_ror:1 row_mask:0xf bank_mask:0xf
	v_cndmask_b32_e64 v101, v169, v93, s[10:11]
	v_fma_f32 v99, v145, v99, v103
	v_fma_f32 v101, v137, v101, v99
	v_cndmask_b32_e64 v99, v90, v166, s[8:9]
	v_mov_b32_dpp v91, v172 row_ror:2 row_mask:0xf bank_mask:0xf
	v_mov_b32_dpp v87, v173 row_ror:1 row_mask:0xf bank_mask:0xf
	v_fma_f32 v166, v150, v172, v154
	v_pk_mul_f32 v[232:233], v[80:81], v[198:199] op_sel_hi:[1,0]
	v_fma_f32 v99, v146, v99, v166
	v_cndmask_b32_e64 v103, v167, v91, s[10:11]
	v_fma_f32 v166, v138, v103, v99
	v_cndmask_b32_e64 v99, v87, v163, s[8:9]
	v_mov_b32_dpp v89, v173 row_ror:2 row_mask:0xf bank_mask:0xf
	v_mov_b32_dpp v86, v232 row_ror:1 row_mask:0xf bank_mask:0xf
	v_fma_f32 v163, v151, v173, v155
	v_fma_f32 v99, v147, v99, v163
	v_cndmask_b32_e64 v103, v165, v89, s[10:11]
	v_mov_b32_dpp v88, v232 row_ror:2 row_mask:0xf bank_mask:0xf
	v_fma_f32 v163, v139, v103, v99
	v_cndmask_b32_e64 v99, v86, v162, s[8:9]
	v_pk_mul_f32 v[230:231], v[82:83], v[198:199] op_sel_hi:[1,0]
	v_mov_b32_dpp v84, v233 row_ror:1 row_mask:0xf bank_mask:0xf
	v_cndmask_b32_e64 v103, v164, v88, s[10:11]
	v_fma_f32 v162, v128, v232, v132
	v_mov_b32_dpp v85, v233 row_ror:2 row_mask:0xf bank_mask:0xf
	v_fma_f32 v99, v124, v99, v162
	v_mov_b32_dpp v82, v230 row_ror:1 row_mask:0xf bank_mask:0xf
	v_fma_f32 v99, v120, v103, v99
	v_cndmask_b32_e64 v103, v84, v160, s[8:9]
	v_mov_b32_dpp v83, v230 row_ror:2 row_mask:0xf bank_mask:0xf
	v_mov_b32_dpp v80, v231 row_ror:1 row_mask:0xf bank_mask:0xf
	v_cndmask_b32_e64 v160, v161, v85, s[10:11]
	v_fma_f32 v161, v129, v233, v133
	v_cndmask_b32_e64 v100, v82, v100, s[8:9]
	v_fma_f32 v103, v125, v103, v161
	v_mov_b32_dpp v81, v231 row_ror:2 row_mask:0xf bank_mask:0xf
	v_fma_f32 v103, v121, v160, v103
	v_cndmask_b32_e64 v102, v102, v83, s[10:11]
	v_fma_f32 v160, v130, v230, v134
	v_cndmask_b32_e64 v96, v80, v96, s[8:9]
	v_fma_f32 v100, v126, v100, v160
	v_cndmask_b32_e64 v98, v98, v81, s[10:11]
	v_fma_f32 v100, v122, v102, v100
	v_fma_f32 v102, v131, v231, v135
	s_nop 0
	v_fma_f32 v96, v127, v96, v102
	s_nop 0
	v_fma_f32 v96, v123, v98, v96
	v_add_u32_e32 v98, s71, v213
	v_cmp_gt_i32_e32 vcc, s68, v98
	s_and_b64 s[0:1], s[52:53], vcc
	v_add_u32_e32 v195, s59, v98
	s_and_saveexec_b64 s[64:65], s[0:1]
	s_cbranch_execz .LBB0_902
	v_mul_f32_e32 v98, 0xbfb8aa3b, v163
	v_exp_f32_e32 v98, v98
	s_nop 0
	v_add_f32_e32 v98, 1.0, v98
	v_rcp_f32_e32 v98, v98
	s_nop 0
	v_mul_f32_e32 v98, v163, v98
	v_mul_f32_e32 v98, v98, v96
	v_mul_f32_e32 v96, 0xbfb8aa3b, v166
	v_exp_f32_e32 v96, v96
	s_nop 0
	v_add_f32_e32 v96, 1.0, v96
	v_rcp_f32_e32 v96, v96
	s_nop 0
	v_mul_f32_e32 v96, v166, v96
	v_mul_f32_e32 v100, v96, v100
	v_mul_f32_e32 v96, 0xbfb8aa3b, v101
	v_exp_f32_e32 v96, v96
	s_nop 0
	v_add_f32_e32 v96, 1.0, v96
	v_rcp_f32_e32 v96, v96
	s_nop 0
	v_mul_f32_e32 v96, v101, v96
	v_mul_f32_e32 v101, 0xbfb8aa3b, v97
	v_exp_f32_e32 v101, v101
	v_mul_f32_e32 v96, v96, v103
	v_add_f32_e32 v101, 1.0, v101
	v_rcp_f32_e32 v101, v101
	s_nop 0
	v_mul_f32_e32 v97, v97, v101
	v_mul_f32_e32 v97, v97, v99
	v_cvt_pk_bf16_f32 v96, v97, v96
	v_cvt_pk_bf16_f32 v97, v100, v98
	v_mov_b64_e32 v[98:99], s[36:37]
	v_mad_i64_i32 v[98:99], s[72:73], v195, s69, v[98:99]
	v_lshl_add_u64 v[98:99], v[192:193], 1, v[98:99]
	global_store_dwordx2 v[98:99], v[96:97], off

; #define PG8_LAS __attribute__((address_space(3)))
; __device__ __forceinline__ unsigned cvt_pk_bf16(float lo, float hi) { unsigned r; asm volatile("v_cvt_pk_bf16_f32 %0, %1, %2" : "=v"(r) : "v"(lo), "v"(hi)); return r; }
;     __device__ __forceinline__ void operator()(const f32x4 (&acc)[2][2][4][2], const Unit& u, int wr, int wc, int fr, int fq) const {
;     ...
;             for (int ai = 0; ai < 2; ++ai) {
;                 f32x4 pr1[2] = {zero4, zero4}, pr2[2] = {zero4, zero4};
;                 const bool hasprev = (wr == 1) || (ai == 1);
;                 const int pg = (wr == 1) ? ai * 2 : (ai - 1) * 2 + 1;
;                 if (hasprev && fr < 2) {
; #pragma unroll
;                     for (int bj = 0; bj < 2; ++bj) {
;                         pr2[bj] = *(const PG8_LAS f32x4*)(xch + ((pg * 2 + fr) * 256 + bj * 128 + colx + n * 4));
;                         pr1[bj] = *(const PG8_LAS f32x4*)(xch + ((pg * 2 + 1) * 256 + bj * 128 + colx + n * 4)); }
;                 }
; #pragma unroll
;                 for (int m = 0; m < 4; ++m) {
;                     f32x4 cur[2] = {acc[ai][0][m][n] * r2v[ai][m], acc[ai][1][m][n] * r2v[ai][m]};
;                     if (first && ai == 0 && wr == 0 && m == 0 && fr < 2) { cur[0] = zero4; cur[1] = zero4; }
;                     f32x4 r1[2], r2[2], av[2];
; #pragma unroll
;                     for (int bj = 0; bj < 2; ++bj)
; #pragma unroll
;                         for (int e = 0; e < 4; ++e) { r1[bj][e] = dpp_ror1(cur[bj][e]); r2[bj][e] = dpp_ror2(cur[bj][e]); }
; #pragma unroll
;                     for (int bj = 0; bj < 2; ++bj)
; #pragma unroll
;                         for (int e = 0; e < 4; ++e) { const float p1 = fr >= 1 ? r1[bj][e] : pr1[bj][e], p2 = fr >= 2 ? r2[bj][e] : pr2[bj][e];
;                             av[bj][e] = fma_s(w0[bj][e], p2, fma_s(w1[bj][e], p1, fma_s(w2[bj][e], cur[bj][e], bb[bj][e]))); }
;                     float o[4];
; #pragma unroll
;                     for (int e = 0; e < 4; ++e) o[e] = av[0][e] * sigmoid_f(av[0][e]) * av[1][e];
;                     const int lr = ai * HALF + wr * 64 + m * 16 + fr, t = t0 + lr;
;                     if (lr >= 2 && t < 4096) { u32x2 w; w.x = cvt_pk_bf16(o[0], o[1]); w.y = cvt_pk_bf16(o[2], o[3]);
;                         *(u32x2*)(gout + (size_t)(b * 4096 + t) * FF + j0 + n * 4) = w; }
.LBB0_906:
	s_or_b64 exec, exec, s[76:77]
	v_fmamk_f32 v202, v248, 0x3a000000, v224
	v_mul_f32_e32 v203, 0x4b800000, v202
	v_cmp_gt_f32_e32 vcc, s35, v202
	s_nop 1
	v_cndmask_b32_e32 v202, v202, v203, vcc
	v_rsq_f32_e32 v202, v202
	s_nop 0
	v_mul_f32_e32 v203, 0x45800000, v202
	v_cndmask_b32_e32 v202, v202, v203, vcc
	v_pk_mul_f32 v[238:239], v[156:157], v[202:203] op_sel_hi:[1,0]
	v_pk_mul_f32 v[242:243], v[140:141], v[202:203] op_sel_hi:[1,0]
	v_pk_mul_f32 v[236:237], v[158:159], v[202:203] op_sel_hi:[1,0]
	v_mov_b32_dpp v234, v238 row_ror:1 row_mask:0xf bank_mask:0xf
	v_mov_b32_dpp v235, v238 row_ror:2 row_mask:0xf bank_mask:0xf
	s_waitcnt lgkmcnt(1)
	v_cndmask_b32_e64 v140, v234, v168, s[8:9]
	v_mov_b32_dpp v232, v239 row_ror:1 row_mask:0xf bank_mask:0xf
	v_cndmask_b32_e64 v141, v172, v235, s[10:11]
	v_fma_f32 v168, v148, v238, v152
	v_mov_b32_dpp v233, v239 row_ror:2 row_mask:0xf bank_mask:0xf
	v_fma_f32 v140, v144, v140, v168
	v_mov_b32_dpp v230, v236 row_ror:1 row_mask:0xf bank_mask:0xf
	v_fma_f32 v140, v136, v141, v140
	v_cndmask_b32_e64 v141, v232, v169, s[8:9]
	v_cndmask_b32_e64 v168, v173, v233, s[10:11]
	v_fma_f32 v169, v149, v239, v153
	v_fma_f32 v141, v145, v141, v169
	v_mov_b32_dpp v231, v236 row_ror:2 row_mask:0xf bank_mask:0xf
	v_fma_f32 v168, v137, v168, v141
	v_cndmask_b32_e64 v141, v230, v170, s[8:9]
	v_mov_b32_dpp v206, v237 row_ror:1 row_mask:0xf bank_mask:0xf
	v_cndmask_b32_e64 v169, v174, v231, s[10:11]
	v_fma_f32 v170, v150, v236, v154
	v_pk_mul_f32 v[240:241], v[142:143], v[202:203] op_sel_hi:[1,0]
	v_fma_f32 v141, v146, v141, v170
	v_mov_b32_dpp v229, v237 row_ror:2 row_mask:0xf bank_mask:0xf
	v_fma_f32 v169, v138, v169, v141
	v_cndmask_b32_e64 v141, v206, v171, s[8:9]
	v_mov_b32_dpp v203, v242 row_ror:1 row_mask:0xf bank_mask:0xf
	v_cndmask_b32_e64 v170, v175, v229, s[10:11]
	v_fma_f32 v171, v151, v237, v155
	v_mov_b32_dpp v207, v242 row_ror:2 row_mask:0xf bank_mask:0xf
	v_fma_f32 v141, v147, v141, v171
	v_fma_f32 v170, v139, v170, v141
	s_waitcnt lgkmcnt(0)
	v_cndmask_b32_e64 v141, v203, v160, s[8:9]
	v_mov_b32_dpp v158, v243 row_ror:1 row_mask:0xf bank_mask:0xf
	v_cndmask_b32_e64 v160, v164, v207, s[10:11]
	v_fma_f32 v164, v128, v242, v132
	v_mov_b32_dpp v159, v243 row_ror:2 row_mask:0xf bank_mask:0xf
	v_fma_f32 v141, v124, v141, v164
	v_fma_f32 v160, v120, v160, v141
	v_cndmask_b32_e64 v141, v158, v161, s[8:9]
	v_mov_b32_dpp v156, v240 row_ror:1 row_mask:0xf bank_mask:0xf
	v_cndmask_b32_e64 v161, v165, v159, s[10:11]
	v_fma_f32 v164, v129, v243, v133
	v_mov_b32_dpp v157, v240 row_ror:2 row_mask:0xf bank_mask:0xf
	v_fma_f32 v141, v125, v141, v164
	v_fma_f32 v161, v121, v161, v141
	v_cndmask_b32_e64 v141, v156, v162, s[8:9]
	v_mov_b32_dpp v142, v241 row_ror:1 row_mask:0xf bank_mask:0xf
	v_cndmask_b32_e64 v162, v166, v157, s[10:11]
	v_fma_f32 v164, v130, v240, v134
	v_mov_b32_dpp v143, v241 row_ror:2 row_mask:0xf bank_mask:0xf
	v_fma_f32 v141, v126, v141, v164
	v_fma_f32 v164, v131, v241, v135
	s_nop 0
	v_fma_f32 v162, v122, v162, v141
	v_cndmask_b32_e64 v141, v142, v163, s[8:9]
	v_cndmask_b32_e64 v163, v167, v143, s[10:11]
	v_fma_f32 v141, v127, v141, v164
	s_nop 0
	v_fma_f32 v163, v123, v163, v141
	v_add_u32_e32 v141, 0x80, v201
	v_cmp_gt_i32_e32 vcc, s68, v141
	s_and_b64 s[76:77], s[4:5], vcc
	v_add_u32_e32 v141, s59, v141
	s_and_saveexec_b64 s[82:83], s[76:77]
	s_cbranch_execz .LBB0_908
	v_mul_f32_e32 v164, 0xbfb8aa3b, v170
	v_exp_f32_e32 v164, v164
	s_nop 0
	v_add_f32_e32 v164, 1.0, v164
	v_rcp_f32_e32 v164, v164
	s_nop 0
	v_mul_f32_e32 v164, v170, v164
	v_mul_f32_e32 v163, v164, v163
	v_mul_f32_e32 v164, 0xbfb8aa3b, v169
	v_exp_f32_e32 v164, v164
	s_nop 0
	v_add_f32_e32 v164, 1.0, v164
	v_rcp_f32_e32 v164, v164
	s_nop 0
	v_mul_f32_e32 v164, v169, v164
	v_mul_f32_e32 v162, v164, v162
	v_mul_f32_e32 v164, 0xbfb8aa3b, v168
	v_exp_f32_e32 v164, v164
	s_nop 0
	v_add_f32_e32 v164, 1.0, v164
	v_rcp_f32_e32 v164, v164
	s_nop 0
	v_mul_f32_e32 v164, v168, v164
	v_mul_f32_e32 v161, v164, v161
	v_mul_f32_e32 v164, 0xbfb8aa3b, v140
	v_exp_f32_e32 v164, v164
	s_nop 0
	v_add_f32_e32 v164, 1.0, v164
	v_rcp_f32_e32 v164, v164
	s_nop 0
	v_mul_f32_e32 v140, v140, v164
	v_mul_f32_e32 v140, v140, v160
	v_cvt_pk_bf16_f32 v160, v140, v161
	v_cvt_pk_bf16_f32 v161, v162, v163
	v_mov_b64_e32 v[162:163], s[36:37]
	v_mad_i64_i32 v[162:163], s[72:73], v141, s69, v[162:163]
	v_lshl_add_u64 v[162:163], v[192:193], 1, v[162:163]
	global_store_dwordx2 v[162:163], v[160:161], off
; __device__ __forceinline__ unsigned cvt_pk_bf16(float lo, float hi) { unsigned r; asm volatile("v_cvt_pk_bf16_f32 %0, %1, %2" : "=v"(r) : "v"(lo), "v"(hi)); return r; }
; __device__ __forceinline__ float sigmoid_f(float x) { return __builtin_amdgcn_rcpf(1.0f + __builtin_amdgcn_exp2f(-1.4426950408889634f * x)); }
; __device__ __forceinline__ float dpp_ror1(float v) { return __builtin_bit_cast(float, __builtin_amdgcn_update_dpp(0, __builtin_bit_cast(int, v), 0x121, 0xf, 0xf, false)); }
; __device__ __forceinline__ float dpp_ror2(float v) { return __builtin_bit_cast(float, __builtin_amdgcn_update_dpp(0, __builtin_bit_cast(int, v), 0x122, 0xf, 0xf, false)); }
; __device__ __forceinline__ float fma_s(float a, float b, float c) { float r; asm("v_fma_f32 %0, %1, %2, %3" : "=v"(r) : "v"(a), "v"(b), "v"(c)); return r; }
;     __device__ __forceinline__ void operator()(const f32x4 (&acc)[2][2][4][2], const Unit& u, int wr, int wc, int fr, int fq) const {
;     ...
;                 for (int m = 0; m < 4; ++m) {
;                     f32x4 cur[2] = {acc[ai][0][m][n] * r2v[ai][m], acc[ai][1][m][n] * r2v[ai][m]};
;                     if (first && ai == 0 && wr == 0 && m == 0 && fr < 2) { cur[0] = zero4; cur[1] = zero4; }
;                     f32x4 r1[2], r2[2], av[2];
; #pragma unroll
;                     for (int bj = 0; bj < 2; ++bj)
; #pragma unroll
;                         for (int e = 0; e < 4; ++e) { r1[bj][e] = dpp_ror1(cur[bj][e]); r2[bj][e] = dpp_ror2(cur[bj][e]); }
; #pragma unroll
;                     for (int bj = 0; bj < 2; ++bj)
; #pragma unroll
;                         for (int e = 0; e < 4; ++e) { const float p1 = fr >= 1 ? r1[bj][e] : pr1[bj][e], p2 = fr >= 2 ? r2[bj][e] : pr2[bj][e];
;                             av[bj][e] = fma_s(w0[bj][e], p2, fma_s(w1[bj][e], p1, fma_s(w2[bj][e], cur[bj][e], bb[bj][e]))); }
;                     float o[4];
; #pragma unroll
;                     for (int e = 0; e < 4; ++e) o[e] = av[0][e] * sigmoid_f(av[0][e]) * av[1][e];
;                     const int lr = ai * HALF + wr * 64 + m * 16 + fr, t = t0 + lr;
;                     if (lr >= 2 && t < 4096) { u32x2 w; w.x = cvt_pk_bf16(o[0], o[1]); w.y = cvt_pk_bf16(o[2], o[3]);
;                         *(u32x2*)(gout + (size_t)(b * 4096 + t) * FF + j0 + n * 4) = w; }
.LBB0_908:
	s_or_b64 exec, exec, s[82:83]
	v_fmamk_f32 v140, v249, 0x3a000000, v224
	v_mul_f32_e32 v160, 0x4b800000, v140
	v_cmp_gt_f32_e32 vcc, s35, v140
	s_nop 1
	v_cndmask_b32_e32 v140, v140, v160, vcc
	v_rsq_f32_e32 v140, v140
	s_nop 0
	v_mul_f32_e32 v160, 0x45800000, v140
	v_cndmask_b32_e32 v140, v140, v160, vcc
	v_pk_mul_f32 v[170:171], v[116:117], v[140:141] op_sel_hi:[1,0]
	v_pk_mul_f32 v[236:237], v[112:113], v[140:141] op_sel_hi:[1,0]
	v_pk_mul_f32 v[172:173], v[118:119], v[140:141] op_sel_hi:[1,0]
	v_mov_b32_dpp v168, v170 row_ror:1 row_mask:0xf bank_mask:0xf
	v_mov_b32_dpp v169, v170 row_ror:2 row_mask:0xf bank_mask:0xf
	v_cndmask_b32_e64 v112, v168, v234, s[8:9]
	v_mov_b32_dpp v166, v171 row_ror:1 row_mask:0xf bank_mask:0xf
	v_cndmask_b32_e64 v113, v235, v169, s[10:11]
	v_fma_f32 v170, v148, v170, v152
	v_mov_b32_dpp v167, v171 row_ror:2 row_mask:0xf bank_mask:0xf
	v_fma_f32 v112, v144, v112, v170
	v_mov_b32_dpp v164, v172 row_ror:1 row_mask:0xf bank_mask:0xf
	v_fma_f32 v112, v136, v113, v112
	v_cndmask_b32_e64 v113, v166, v232, s[8:9]
	v_fma_f32 v171, v149, v171, v153
	v_fma_f32 v113, v145, v113, v171
	v_cndmask_b32_e64 v170, v233, v167, s[10:11]
	v_fma_f32 v171, v137, v170, v113
	v_cndmask_b32_e64 v113, v164, v230, s[8:9]
	v_mov_b32_dpp v165, v172 row_ror:2 row_mask:0xf bank_mask:0xf
	v_mov_b32_dpp v161, v173 row_ror:1 row_mask:0xf bank_mask:0xf
	v_fma_f32 v172, v150, v172, v154
	v_fma_f32 v113, v146, v113, v172
	v_cndmask_b32_e64 v170, v231, v165, s[10:11]
	v_fma_f32 v172, v138, v170, v113
	v_cndmask_b32_e64 v113, v161, v206, s[8:9]
	v_mov_b32_dpp v163, v173 row_ror:2 row_mask:0xf bank_mask:0xf
	v_mov_b32_dpp v160, v236 row_ror:1 row_mask:0xf bank_mask:0xf
	v_fma_f32 v173, v151, v173, v155
	v_fma_f32 v113, v147, v113, v173
	v_cndmask_b32_e64 v170, v229, v163, s[10:11]
	v_mov_b32_dpp v162, v236 row_ror:2 row_mask:0xf bank_mask:0xf
	v_fma_f32 v173, v139, v170, v113
	v_cndmask_b32_e64 v113, v160, v203, s[8:9]
	v_mov_b32_dpp v118, v237 row_ror:1 row_mask:0xf bank_mask:0xf
	v_cndmask_b32_e64 v170, v207, v162, s[10:11]
	v_fma_f32 v203, v128, v236, v132
	v_pk_mul_f32 v[174:175], v[114:115], v[140:141] op_sel_hi:[1,0]
	v_fma_f32 v113, v124, v113, v203
	v_mov_b32_dpp v119, v237 row_ror:2 row_mask:0xf bank_mask:0xf
	v_fma_f32 v170, v120, v170, v113
	v_cndmask_b32_e64 v113, v118, v158, s[8:9]
	v_mov_b32_dpp v116, v174 row_ror:1 row_mask:0xf bank_mask:0xf
	v_cndmask_b32_e64 v158, v159, v119, s[10:11]
	v_fma_f32 v159, v129, v237, v133
	v_mov_b32_dpp v117, v174 row_ror:2 row_mask:0xf bank_mask:0xf
	v_fma_f32 v113, v125, v113, v159
	v_fma_f32 v158, v121, v158, v113
	v_cndmask_b32_e64 v113, v116, v156, s[8:9]
	v_mov_b32_dpp v114, v175 row_ror:1 row_mask:0xf bank_mask:0xf
	v_cndmask_b32_e64 v156, v157, v117, s[10:11]
	v_fma_f32 v157, v130, v174, v134
	v_mov_b32_dpp v115, v175 row_ror:2 row_mask:0xf bank_mask:0xf
	v_fma_f32 v113, v126, v113, v157
	v_readlane_b32 s12, v254, 22
	v_fma_f32 v156, v122, v156, v113
	v_cndmask_b32_e64 v113, v114, v142, s[8:9]
	v_cndmask_b32_e64 v142, v143, v115, s[10:11]
	v_fma_f32 v143, v131, v175, v135
	v_readlane_b32 s13, v254, 23
	v_fma_f32 v113, v127, v113, v143
	s_nop 0
	v_fma_f32 v142, v123, v142, v113
	v_add_u32_e32 v113, 0x90, v201
	v_cmp_gt_i32_e32 vcc, s68, v113
	s_and_b64 s[82:83], s[12:13], vcc
	v_add_u32_e32 v113, s59, v113
	s_and_saveexec_b64 s[84:85], s[82:83]
	s_cbranch_execz .LBB0_910
	v_mul_f32_e32 v143, 0xbfb8aa3b, v173
	v_exp_f32_e32 v143, v143
	v_mul_f32_e32 v157, 0xbfb8aa3b, v112
	v_exp_f32_e32 v157, v157
	v_add_f32_e32 v143, 1.0, v143
	v_rcp_f32_e32 v143, v143
	v_add_f32_e32 v157, 1.0, v157
	v_rcp_f32_e32 v157, v157
	v_mul_f32_e32 v143, v173, v143
	v_mul_f32_e32 v143, v143, v142
	v_mul_f32_e32 v142, 0xbfb8aa3b, v172
	v_exp_f32_e32 v142, v142
	v_mul_f32_e32 v112, v112, v157
	v_mul_f32_e32 v112, v112, v170
	v_add_f32_e32 v142, 1.0, v142
	v_rcp_f32_e32 v142, v142
	s_nop 0
	v_mul_f32_e32 v142, v172, v142
	v_mul_f32_e32 v156, v142, v156
	v_mul_f32_e32 v142, 0xbfb8aa3b, v171
	v_exp_f32_e32 v142, v142
	s_nop 0
	v_add_f32_e32 v142, 1.0, v142
	v_rcp_f32_e32 v142, v142
	s_nop 0
	v_mul_f32_e32 v142, v171, v142
	v_mul_f32_e32 v142, v142, v158
	v_cvt_pk_bf16_f32 v142, v112, v142
	v_cvt_pk_bf16_f32 v143, v156, v143
	v_mov_b64_e32 v[156:157], s[36:37]
	v_mad_i64_i32 v[156:157], s[72:73], v113, s69, v[156:157]
	v_lshl_add_u64 v[156:157], v[192:193], 1, v[156:157]
	global_store_dwordx2 v[156:157], v[142:143], off
; __device__ __forceinline__ unsigned cvt_pk_bf16(float lo, float hi) { unsigned r; asm volatile("v_cvt_pk_bf16_f32 %0, %1, %2" : "=v"(r) : "v"(lo), "v"(hi)); return r; }
; __device__ __forceinline__ float sigmoid_f(float x) { return __builtin_amdgcn_rcpf(1.0f + __builtin_amdgcn_exp2f(-1.4426950408889634f * x)); }
; __device__ __forceinline__ float dpp_ror1(float v) { return __builtin_bit_cast(float, __builtin_amdgcn_update_dpp(0, __builtin_bit_cast(int, v), 0x121, 0xf, 0xf, false)); }
;     __device__ __forceinline__ void operator()(const f32x4 (&acc)[2][2][4][2], const Unit& u, int wr, int wc, int fr, int fq) const {
;     ...
;         const int b = u.pm / 17, ti = u.pm % 17, t0 = 254 * ti - 2;
;         const int colx = wc * 32 + fq * 8, j0 = u.pn * 128 + colx;
;         float r2v[2][4]; f32x4 wts[2][2][4];
; #pragma unroll
;         for (int ai = 0; ai < 2; ++ai)
; #pragma unroll
;             for (int m = 0; m < 4; ++m) { int t = t0 + ai * HALF + wr * 64 + m * 16 + fr; t = t < 0 ? 0 : (t > 4095 ? 4095 : t); r2v[ai][m] = rowss[b * 4096 + t]; }
;     ...
;                 for (int m = 0; m < 4; ++m) {
;                     f32x4 cur[2] = {acc[ai][0][m][n] * r2v[ai][m], acc[ai][1][m][n] * r2v[ai][m]};
;                     if (first && ai == 0 && wr == 0 && m == 0 && fr < 2) { cur[0] = zero4; cur[1] = zero4; }
;                     f32x4 r1[2], r2[2], av[2];
; #pragma unroll
;                     for (int bj = 0; bj < 2; ++bj)
; #pragma unroll
;                         for (int e = 0; e < 4; ++e) { r1[bj][e] = dpp_ror1(cur[bj][e]); r2[bj][e] = dpp_ror2(cur[bj][e]); }
; #pragma unroll
;                     for (int bj = 0; bj < 2; ++bj)
; #pragma unroll
;                         for (int e = 0; e < 4; ++e) { const float p1 = fr >= 1 ? r1[bj][e] : pr1[bj][e], p2 = fr >= 2 ? r2[bj][e] : pr2[bj][e];
;                             av[bj][e] = fma_s(w0[bj][e], p2, fma_s(w1[bj][e], p1, fma_s(w2[bj][e], cur[bj][e], bb[bj][e]))); }
;                     float o[4];
; #pragma unroll
;                     for (int e = 0; e < 4; ++e) o[e] = av[0][e] * sigmoid_f(av[0][e]) * av[1][e];
;                     const int lr = ai * HALF + wr * 64 + m * 16 + fr, t = t0 + lr;
;                     if (lr >= 2 && t < 4096) { u32x2 w; w.x = cvt_pk_bf16(o[0], o[1]); w.y = cvt_pk_bf16(o[2], o[3]);
;                         *(u32x2*)(gout + (size_t)(b * 4096 + t) * FF + j0 + n * 4) = w; }
.LBB0_910:
	s_or_b64 exec, exec, s[84:85]
	v_fmamk_f32 v112, v250, 0x3a000000, v224
	s_and_b64 s[100:101], exec, s[22:23]
	s_cbranch_scc1 .Lp9pre_skip
	s_mul_hi_i32 s100, s70, 0x78787879
	s_lshr_b32 s101, s100, 31
	s_ashr_i32 s100, s100, 3
	s_add_i32 s100, s100, s101
	s_mul_i32 s101, s100, 17
	s_sub_i32 s101, s70, s101
	s_mulk_i32 s101, 0xfe
	s_add_i32 s101, s101, -2
	s_lshl_b32 s100, s100, 12
	v_add_u32_e32 v252, s101, v208
	v_med3_i32 v253, v252, 0, v225
	v_or_b32_e32 v253, s100, v253
	v_lshlrev_b32_e32 v253, 2, v253
	global_load_dword v244, v253, s[40:41]
	v_max_i32_e32 v253, -16, v252
	v_add_u32_e32 v253, 16, v253
	v_min_u32_e32 v253, 0xfff, v253
	v_or_b32_e32 v253, s100, v253
	v_lshlrev_b32_e32 v253, 2, v253
	global_load_dword v245, v253, s[40:41]
	v_max_i32_e32 v253, 0xffffffe0, v252
	v_add_u32_e32 v253, 32, v253
	v_min_u32_e32 v253, 0xfff, v253
	v_or_b32_e32 v253, s100, v253
	v_lshlrev_b32_e32 v253, 2, v253
	global_load_dword v246, v253, s[40:41]
	v_max_i32_e32 v253, 0xffffffd0, v252
	v_add_u32_e32 v253, 48, v253
	v_min_u32_e32 v253, 0xfff, v253
	v_or_b32_e32 v253, s100, v253
	v_lshlrev_b32_e32 v253, 2, v253
	global_load_dword v247, v253, s[40:41]
	v_max_i32_e32 v253, 0xffffff80, v252
	v_add_u32_e32 v253, 0x80, v253
	v_min_u32_e32 v253, 0xfff, v253
	v_or_b32_e32 v253, s100, v253
	v_lshlrev_b32_e32 v253, 2, v253
	global_load_dword v248, v253, s[40:41]
	v_max_i32_e32 v253, 0xffffff70, v252
	v_add_u32_e32 v253, 0x90, v253
	v_min_u32_e32 v253, 0xfff, v253
	v_or_b32_e32 v253, s100, v253
	v_lshlrev_b32_e32 v253, 2, v253
	global_load_dword v249, v253, s[40:41]
	v_max_i32_e32 v253, 0xffffff60, v252
	v_add_u32_e32 v253, 0xa0, v253
	v_min_u32_e32 v253, 0xfff, v253
	v_or_b32_e32 v253, s100, v253
	v_lshlrev_b32_e32 v253, 2, v253
	global_load_dword v250, v253, s[40:41]
	v_max_i32_e32 v253, 0xffffff50, v252
	v_add_u32_e32 v253, 0xb0, v253
	v_min_u32_e32 v253, 0xfff, v253
	v_or_b32_e32 v253, s100, v253
	v_lshlrev_b32_e32 v253, 2, v253
	global_load_dword v251, v253, s[40:41]
.Lp9pre_skip:
	v_mul_f32_e32 v142, 0x4b800000, v112
	v_cmp_gt_f32_e32 vcc, s35, v112
	s_nop 1
	v_cndmask_b32_e32 v112, v112, v142, vcc
	v_rsq_f32_e32 v112, v112
	s_nop 0
	v_mul_f32_e32 v142, 0x45800000, v112
	v_cndmask_b32_e32 v112, v112, v142, vcc
	v_pk_mul_f32 v[174:175], v[108:109], v[112:113] op_sel_hi:[1,0]
	v_pk_mul_f32 v[172:173], v[110:111], v[112:113] op_sel_hi:[1,0]
	s_nop 0
	v_mov_b32_dpp v170, v174 row_ror:1 row_mask:0xf bank_mask:0xf
	v_mov_b32_dpp v171, v174 row_ror:2 row_mask:0xf bank_mask:0xf
	v_mov_b32_dpp v158, v175 row_ror:1 row_mask:0xf bank_mask:0xf
	v_cndmask_b32_e64 v168, v170, v168, s[8:9]
	v_mov_b32_dpp v159, v175 row_ror:2 row_mask:0xf bank_mask:0xf
	v_mov_b32_dpp v156, v172 row_ror:1 row_mask:0xf bank_mask:0xf
	v_cndmask_b32_e64 v169, v169, v171, s[10:11]
	v_fma_f32 v174, v148, v174, v152
	v_cndmask_b32_e64 v166, v158, v166, s[8:9]
	v_fma_f32 v168, v144, v168, v174
	v_pk_mul_f32 v[228:229], v[104:105], v[112:113] op_sel_hi:[1,0]
	v_mov_b32_dpp v157, v172 row_ror:2 row_mask:0xf bank_mask:0xf
	v_mov_b32_dpp v111, v173 row_ror:1 row_mask:0xf bank_mask:0xf
	v_fma_f32 v168, v136, v169, v168
	v_cndmask_b32_e64 v167, v167, v159, s[10:11]
	v_fma_f32 v169, v149, v175, v153
	v_cndmask_b32_e64 v164, v156, v164, s[8:9]
	v_fma_f32 v166, v145, v166, v169
	v_mov_b32_dpp v143, v173 row_ror:2 row_mask:0xf bank_mask:0xf
	v_mov_b32_dpp v110, v228 row_ror:1 row_mask:0xf bank_mask:0xf
	v_fma_f32 v166, v137, v167, v166
	v_cndmask_b32_e64 v165, v165, v157, s[10:11]
	v_fma_f32 v167, v150, v172, v154
	v_cndmask_b32_e64 v161, v111, v161, s[8:9]
	v_fma_f32 v164, v146, v164, v167
	v_pk_mul_f32 v[206:207], v[106:107], v[112:113] op_sel_hi:[1,0]
	v_mov_b32_dpp v142, v228 row_ror:2 row_mask:0xf bank_mask:0xf
	v_mov_b32_dpp v108, v229 row_ror:1 row_mask:0xf bank_mask:0xf
	v_fma_f32 v164, v138, v165, v164
	v_cndmask_b32_e64 v163, v163, v143, s[10:11]
	v_fma_f32 v165, v151, v173, v155
	v_cndmask_b32_e64 v160, v110, v160, s[8:9]
	v_fma_f32 v161, v147, v161, v165
	v_mov_b32_dpp v109, v229 row_ror:2 row_mask:0xf bank_mask:0xf
	v_mov_b32_dpp v106, v206 row_ror:1 row_mask:0xf bank_mask:0xf
	v_fma_f32 v161, v139, v163, v161
	v_cndmask_b32_e64 v162, v162, v142, s[10:11]
	v_fma_f32 v163, v128, v228, v132
	v_cndmask_b32_e64 v118, v108, v118, s[8:9]
	v_fma_f32 v160, v124, v160, v163
	v_mov_b32_dpp v107, v206 row_ror:2 row_mask:0xf bank_mask:0xf
	v_mov_b32_dpp v104, v207 row_ror:1 row_mask:0xf bank_mask:0xf
	v_fma_f32 v160, v120, v162, v160
	v_cndmask_b32_e64 v119, v119, v109, s[10:11]
	v_fma_f32 v162, v129, v229, v133
	v_cndmask_b32_e64 v116, v106, v116, s[8:9]
	v_fma_f32 v118, v125, v118, v162
	v_mov_b32_dpp v105, v207 row_ror:2 row_mask:0xf bank_mask:0xf
	v_fma_f32 v118, v121, v119, v118
	v_cndmask_b32_e64 v117, v117, v107, s[10:11]
	v_fma_f32 v119, v130, v206, v134
	v_cndmask_b32_e64 v114, v104, v114, s[8:9]
	v_fma_f32 v116, v126, v116, v119
	v_cndmask_b32_e64 v115, v115, v105, s[10:11]
	v_fma_f32 v116, v122, v117, v116
	v_fma_f32 v117, v131, v207, v135
	v_readlane_b32 s12, v254, 24
	v_fma_f32 v114, v127, v114, v117
	v_readlane_b32 s13, v254, 25
	v_fma_f32 v115, v123, v115, v114
	v_add_u32_e32 v114, 0xa0, v201
	v_cmp_gt_i32_e32 vcc, s68, v114
	s_and_b64 s[84:85], s[12:13], vcc
	v_add_u32_e32 v114, s59, v114
	s_and_saveexec_b64 s[86:87], s[84:85]
	s_cbranch_execz .LBB0_912
	v_mul_f32_e32 v117, 0xbfb8aa3b, v161
	v_exp_f32_e32 v117, v117
	s_nop 0
	v_add_f32_e32 v117, 1.0, v117
	v_rcp_f32_e32 v117, v117
	s_nop 0
	v_mul_f32_e32 v117, v161, v117
	v_mul_f32_e32 v115, v117, v115
	v_mul_f32_e32 v117, 0xbfb8aa3b, v164
	v_exp_f32_e32 v117, v117
	s_nop 0
	v_add_f32_e32 v117, 1.0, v117
	v_rcp_f32_e32 v117, v117
	s_nop 0
	v_mul_f32_e32 v117, v164, v117
	v_mul_f32_e32 v117, v117, v116
	v_mul_f32_e32 v116, 0xbfb8aa3b, v166
	v_exp_f32_e32 v116, v116
	s_nop 0
	v_add_f32_e32 v116, 1.0, v116
	v_rcp_f32_e32 v116, v116
	s_nop 0
	v_mul_f32_e32 v116, v166, v116
	v_mul_f32_e32 v116, v116, v118
	v_mul_f32_e32 v118, 0xbfb8aa3b, v168
	v_exp_f32_e32 v118, v118
	s_nop 0
	v_add_f32_e32 v118, 1.0, v118
	v_rcp_f32_e32 v118, v118
	s_nop 0
	v_mul_f32_e32 v118, v168, v118
	v_mul_f32_e32 v118, v118, v160
	v_cvt_pk_bf16_f32 v116, v118, v116
	v_mov_b64_e32 v[118:119], s[36:37]
	v_mad_i64_i32 v[118:119], s[72:73], v114, s69, v[118:119]
	v_lshl_add_u64 v[118:119], v[192:193], 1, v[118:119]
	v_cvt_pk_bf16_f32 v117, v117, v115
	global_store_dwordx2 v[118:119], v[116:117], off
